# v92: v88 + FoX epilogue dwordx2 gate loads and output stores paired into dwordx4 via v_permlane32_swap
# speedup vs baseline: 1.0152x; 1.0152x over previous
; __device__ __forceinline__ float silu_f(float z) { return z * __builtin_amdgcn_rcpf(1.0f + __builtin_amdgcn_exp2f(-LOG2E * z)); }
; __device__ __forceinline__ float bf_lo(unsigned v) { return __uint_as_float(v << 16); }
; __device__ __forceinline__ float bf_hi(unsigned v) { return __uint_as_float(v & 0xffff0000u); }
; template <int MODE>
; __device__ __forceinline__ void attn_unit(const Params& P, LAS unsigned char* lds, const int b, const int h, const int qb) {
;     ...
;     bf16_t* mix = (bf16_t*)(P.ws + WS_MIX) + (tokbase + q) * DM + colO;
;     const bf16_t* zp = Zb + (size_t)q * RS;
;     const float inv1 = 1.0f / (l1 + __shfl_xor(l1, 32));
;     u32x2 zv[4][4]; f32x4 gv[4][4];
;     if (FOX || mp == 0) {
; #pragma unroll
;         for (int d = 0; d < 4; ++d)
; #pragma unroll
;             for (int a = 0; a < 4; ++a) { const int d0 = 32 * d + 8 * a + 4 * hh; zv[d][a] = *(const u32x2*)(zp + d0); if (!FOX) gv[d][a] = *(const f32x4*)(P.in[I_DON] + d0); }
;     }
;     asm volatile("" ::: "memory");
;     if (FOX) {
; #pragma unroll
;         for (int d = 0; d < 4; ++d)
; #pragma unroll
;             for (int a = 0; a < 4; ++a) { const int d0 = 32 * d + 8 * a + 4 * hh; const u32x2 z2 = zv[d][a];
;                 const float o0 = O[d][4 * a] * inv1 * silu_f(bf_lo(z2.x)), o1 = O[d][4 * a + 1] * inv1 * silu_f(bf_hi(z2.x));
;                 const float o2 = O[d][4 * a + 2] * inv1 * silu_f(bf_lo(z2.y)), o3 = O[d][4 * a + 3] * inv1 * silu_f(bf_hi(z2.y));
;                 u32x2 ov; ov.x = cvt_pk_bf16(o0, o1); ov.y = cvt_pk_bf16(o2, o3); *(u32x2*)(mix + d0) = ov; }
.LBB0_465:
	s_lshr_b32 s0, s12, 3
	s_add_u32 s8, s84, s64
	s_addc_u32 s9, s85, s65
	v_lshl_add_u64 v[2:3], v[182:183], 1, s[8:9]
	v_mov_b32_e32 v97, v1
	v_lshl_add_u64 v[2:3], v[2:3], 0, v[96:97]
	v_mad_i32_i24 v224, v96, -3, 16
	v_ashrrev_i32_e32 v225, 31, v224
	v_lshl_add_u64 v[224:225], v[2:3], 0, v[224:225]
	global_load_dwordx4 v[212:215], v[224:225], off
	v_and_b32_e32 v6, 64, v179
	v_xor_b32_e32 v0, 32, v179
	v_add_u32_e32 v6, 64, v6
	v_cmp_lt_i32_e32 vcc, v0, v6
	global_load_dwordx4 v[216:219], v[224:225], off offset:32
	global_load_dwordx4 v[88:91], v[224:225], off offset:64
	global_load_dwordx4 v[84:87], v[224:225], off offset:96
	global_load_dwordx4 v[80:83], v[224:225], off offset:128
	global_load_dwordx4 v[12:15], v[224:225], off offset:160
	global_load_dwordx4 v[8:11], v[224:225], off offset:192
	global_load_dwordx4 v[220:223], v[224:225], off offset:224
	s_nop 0
	v_cndmask_b32_e32 v0, v179, v0, vcc
	v_lshlrev_b32_e32 v0, 2, v0
	ds_bpermute_b32 v0, v0, v191
	s_mov_b32 s1, s13
	s_lshl_b64 s[0:1], s[0:1], 25
	s_add_u32 s0, s20, s0
	v_lshlrev_b64 v[4:5], 12, v[180:181]
	s_addc_u32 s1, s21, s1
	s_waitcnt lgkmcnt(0)
	v_add_f32_e32 v0, v191, v0
	v_lshl_add_u64 v[4:5], s[0:1], 0, v[4:5]
	v_div_scale_f32 v102, s[0:1], v0, v0, 1.0
	v_rcp_f32_e32 v103, v102
	s_lshl_b32 s8, s12, 8
	s_and_b32 s12, s8, 0x700
	v_lshl_add_u64 v[4:5], v[4:5], 0, s[12:13]
	v_lshl_add_u64 v[4:5], v[4:5], 0, v[96:97]
	v_lshl_add_u64 v[226:227], v[4:5], 0, v[96:97]
	v_fma_f32 v97, -v102, v103, 1.0
	v_div_scale_f32 v96, vcc, 1.0, v0, 1.0
	v_fmac_f32_e32 v103, v97, v103
	v_mul_f32_e32 v97, v96, v103
	v_fma_f32 v104, -v102, v97, v96
	v_fmac_f32_e32 v97, v104, v103
	v_fma_f32 v96, -v102, v97, v96
	v_div_fmas_f32 v96, v96, v103, v97
	v_div_fixup_f32 v0, v96, v0, 1.0
	v_pk_mul_f32 v[64:65], v[64:65], v[0:1] op_sel_hi:[1,0]
	v_pk_mul_f32 v[66:67], v[66:67], v[0:1] op_sel_hi:[1,0]
	v_pk_mul_f32 v[68:69], v[68:69], v[0:1] op_sel_hi:[1,0]
	v_pk_mul_f32 v[48:49], v[48:49], v[0:1] op_sel_hi:[1,0]
	v_pk_mul_f32 v[50:51], v[50:51], v[0:1] op_sel_hi:[1,0]
	v_pk_mul_f32 v[52:53], v[52:53], v[0:1] op_sel_hi:[1,0]
	v_pk_mul_f32 v[32:33], v[32:33], v[0:1] op_sel_hi:[1,0]
	v_pk_mul_f32 v[34:35], v[34:35], v[0:1] op_sel_hi:[1,0]
	v_pk_mul_f32 v[36:37], v[36:37], v[0:1] op_sel_hi:[1,0]
	s_mov_b64 s[8:9], 0
	s_waitcnt vmcnt(0)
	v_permlane32_swap_b32 v212, v214
	v_permlane32_swap_b32 v213, v215
	v_mov_b32_e32 v98, v212
	v_mov_b32_e32 v99, v213
	v_mov_b32_e32 v94, v214
	v_mov_b32_e32 v95, v215
	v_permlane32_swap_b32 v216, v218
	v_permlane32_swap_b32 v217, v219
	v_mov_b32_e32 v92, v216
	v_mov_b32_e32 v93, v217
	v_mov_b32_e32 v100, v218
	v_mov_b32_e32 v101, v219
	v_permlane32_swap_b32 v88, v90
	v_permlane32_swap_b32 v89, v91
	v_permlane32_swap_b32 v84, v86
	v_permlane32_swap_b32 v85, v87
	v_permlane32_swap_b32 v80, v82
	v_permlane32_swap_b32 v81, v83
	v_permlane32_swap_b32 v12, v14
	v_permlane32_swap_b32 v13, v15
	v_permlane32_swap_b32 v8, v10
	v_permlane32_swap_b32 v9, v11
	v_permlane32_swap_b32 v220, v222
	v_permlane32_swap_b32 v221, v223
	v_mov_b32_e32 v2, v220
	v_mov_b32_e32 v3, v221
	v_mov_b32_e32 v6, v222
	v_mov_b32_e32 v7, v223
	v_lshlrev_b32_e32 v96, 16, v94
	v_and_b32_e32 v97, 0xffff0000, v94
	v_lshlrev_b32_e32 v94, 16, v95
	v_and_b32_e32 v95, 0xffff0000, v95
	v_mul_f32_e32 v104, 0xbfb8aa3b, v96
	v_mul_f32_e32 v105, 0xbfb8aa3b, v97
	v_mul_f32_e32 v106, 0xbfb8aa3b, v94
	v_mul_f32_e32 v107, 0xbfb8aa3b, v95
	v_exp_f32_e32 v104, v104
	v_exp_f32_e32 v105, v105
	v_exp_f32_e32 v106, v106
	v_exp_f32_e32 v107, v107
	v_add_f32_e32 v104, 1.0, v104
	v_add_f32_e32 v105, 1.0, v105
	v_add_f32_e32 v106, 1.0, v106
	v_add_f32_e32 v107, 1.0, v107
	v_lshlrev_b32_e32 v102, 16, v98
	v_and_b32_e32 v103, 0xffff0000, v98
	v_rcp_f32_e32 v104, v104
	v_rcp_f32_e32 v105, v105
	v_rcp_f32_e32 v106, v106
	v_rcp_f32_e32 v107, v107
	v_lshlrev_b32_e32 v98, 16, v99
	v_and_b32_e32 v99, 0xffff0000, v99
	v_mul_f32_e32 v108, 0xbfb8aa3b, v102
	v_mul_f32_e32 v109, 0xbfb8aa3b, v103
	v_mul_f32_e32 v110, 0xbfb8aa3b, v98
	v_mul_f32_e32 v111, 0xbfb8aa3b, v99
	v_exp_f32_e32 v108, v108
	v_exp_f32_e32 v109, v109
	v_exp_f32_e32 v110, v110
	v_exp_f32_e32 v111, v111
	v_pk_mul_f32 v[96:97], v[104:105], v[96:97]
	v_pk_mul_f32 v[94:95], v[106:107], v[94:95]
	v_pk_mul_f32 v[64:65], v[64:65], v[96:97]
	v_pk_mul_f32 v[66:67], v[66:67], v[94:95]
	v_add_f32_e32 v108, 1.0, v108
	v_add_f32_e32 v109, 1.0, v109
	v_cvt_pk_bf16_f32 v64, v64, v65
	v_cvt_pk_bf16_f32 v65, v66, v67
	v_rcp_f32_e32 v108, v108
	v_mov_b32_e32 v236, v64
	v_mov_b32_e32 v237, v65
	v_rcp_f32_e32 v109, v109
	v_add_f32_e32 v64, 1.0, v110
	v_add_f32_e32 v65, 1.0, v111
	v_rcp_f32_e32 v64, v64
	v_rcp_f32_e32 v65, v65
	v_pk_mul_f32 v[66:67], v[108:109], v[102:103]
	v_pk_mul_f32 v[64:65], v[64:65], v[98:99]
	v_pk_mul_f32 v[66:67], v[68:69], v[66:67]
	v_pk_mul_f32 v[68:69], v[70:71], v[0:1] op_sel_hi:[1,0]
	v_cvt_pk_bf16_f32 v66, v66, v67
	v_pk_mul_f32 v[64:65], v[68:69], v[64:65]
	v_lshlrev_b32_e32 v70, 16, v101
	v_cvt_pk_bf16_f32 v67, v64, v65
	v_lshlrev_b32_e32 v64, 16, v100
	v_mul_f32_e32 v65, 0xbfb8aa3b, v64
	v_mov_b32_e32 v238, v66
	v_mov_b32_e32 v239, v67
	s_nop 1
	v_permlane32_swap_b32 v236, v238
	v_permlane32_swap_b32 v237, v239
	global_store_dwordx4 v[226:227], v[236:239], off
	v_exp_f32_e32 v66, v65
	v_and_b32_e32 v65, 0xffff0000, v100
	v_mul_f32_e32 v67, 0xbfb8aa3b, v65
	v_and_b32_e32 v71, 0xffff0000, v101
	v_exp_f32_e32 v67, v67
	v_pk_mul_f32 v[68:69], v[72:73], v[0:1] op_sel_hi:[1,0]
	v_mul_f32_e32 v72, 0xbfb8aa3b, v70
	v_mul_f32_e32 v73, 0xbfb8aa3b, v71
	v_exp_f32_e32 v72, v72
	v_exp_f32_e32 v73, v73
	v_add_f32_e32 v66, 1.0, v66
	v_add_f32_e32 v67, 1.0, v67
; __device__ __forceinline__ float silu_f(float z) { return z * __builtin_amdgcn_rcpf(1.0f + __builtin_amdgcn_exp2f(-LOG2E * z)); }
; __device__ __forceinline__ float bf_lo(unsigned v) { return __uint_as_float(v << 16); }
; __device__ __forceinline__ float bf_hi(unsigned v) { return __uint_as_float(v & 0xffff0000u); }
; template <int MODE>
; __device__ __forceinline__ void attn_unit(const Params& P, LAS unsigned char* lds, const int b, const int h, const int qb) {
;     ...
;     if (FOX) {
; #pragma unroll
;         for (int d = 0; d < 4; ++d)
; #pragma unroll
;             for (int a = 0; a < 4; ++a) { const int d0 = 32 * d + 8 * a + 4 * hh; const u32x2 z2 = zv[d][a];
;                 const float o0 = O[d][4 * a] * inv1 * silu_f(bf_lo(z2.x)), o1 = O[d][4 * a + 1] * inv1 * silu_f(bf_hi(z2.x));
;                 const float o2 = O[d][4 * a + 2] * inv1 * silu_f(bf_lo(z2.y)), o3 = O[d][4 * a + 3] * inv1 * silu_f(bf_hi(z2.y));
;                 u32x2 ov; ov.x = cvt_pk_bf16(o0, o1); ov.y = cvt_pk_bf16(o2, o3); *(u32x2*)(mix + d0) = ov; }
	v_rcp_f32_e32 v66, v66
	v_rcp_f32_e32 v67, v67
	v_add_f32_e32 v72, 1.0, v72
	v_add_f32_e32 v73, 1.0, v73
	v_rcp_f32_e32 v72, v72
	v_rcp_f32_e32 v73, v73
	v_pk_mul_f32 v[64:65], v[66:67], v[64:65]
	v_pk_mul_f32 v[66:67], v[74:75], v[0:1] op_sel_hi:[1,0]
	v_pk_mul_f32 v[64:65], v[68:69], v[64:65]
	v_pk_mul_f32 v[68:69], v[72:73], v[70:71]
	v_cvt_pk_bf16_f32 v64, v64, v65
	v_pk_mul_f32 v[66:67], v[66:67], v[68:69]
	v_lshlrev_b32_e32 v70, 16, v93
	v_cvt_pk_bf16_f32 v65, v66, v67
	v_mov_b32_e32 v240, v64
	v_mov_b32_e32 v241, v65
	v_lshlrev_b32_e32 v64, 16, v92
	v_mul_f32_e32 v65, 0xbfb8aa3b, v64
	v_exp_f32_e32 v66, v65
	v_and_b32_e32 v65, 0xffff0000, v92
	v_mul_f32_e32 v67, 0xbfb8aa3b, v65
	v_and_b32_e32 v71, 0xffff0000, v93
	v_exp_f32_e32 v67, v67
	v_mul_f32_e32 v72, 0xbfb8aa3b, v70
	v_mul_f32_e32 v73, 0xbfb8aa3b, v71
	v_exp_f32_e32 v72, v72
	v_exp_f32_e32 v73, v73
	v_add_f32_e32 v66, 1.0, v66
	v_add_f32_e32 v67, 1.0, v67
	v_rcp_f32_e32 v66, v66
	v_rcp_f32_e32 v67, v67
	v_add_f32_e32 v72, 1.0, v72
	v_add_f32_e32 v73, 1.0, v73
	v_rcp_f32_e32 v72, v72
	v_rcp_f32_e32 v73, v73
	v_pk_mul_f32 v[68:69], v[76:77], v[0:1] op_sel_hi:[1,0]
	v_pk_mul_f32 v[64:65], v[66:67], v[64:65]
	v_pk_mul_f32 v[66:67], v[78:79], v[0:1] op_sel_hi:[1,0]
	v_pk_mul_f32 v[64:65], v[68:69], v[64:65]
	v_pk_mul_f32 v[68:69], v[72:73], v[70:71]
	v_cvt_pk_bf16_f32 v64, v64, v65
	v_pk_mul_f32 v[66:67], v[66:67], v[68:69]
	v_lshlrev_b32_e32 v68, 16, v91
	v_cvt_pk_bf16_f32 v65, v66, v67
	v_mov_b32_e32 v242, v64
	v_mov_b32_e32 v243, v65
	s_nop 1
	v_permlane32_swap_b32 v240, v242
	v_permlane32_swap_b32 v241, v243
	global_store_dwordx4 v[226:227], v[240:243], off offset:32
	v_lshlrev_b32_e32 v64, 16, v90
	v_mul_f32_e32 v65, 0xbfb8aa3b, v64
	v_exp_f32_e32 v66, v65
	v_and_b32_e32 v65, 0xffff0000, v90
	v_mul_f32_e32 v67, 0xbfb8aa3b, v65
	v_and_b32_e32 v69, 0xffff0000, v91
	v_exp_f32_e32 v67, v67
	v_mul_f32_e32 v70, 0xbfb8aa3b, v68
	v_mul_f32_e32 v71, 0xbfb8aa3b, v69
	v_exp_f32_e32 v70, v70
	v_exp_f32_e32 v71, v71
	v_add_f32_e32 v66, 1.0, v66
	v_add_f32_e32 v67, 1.0, v67
	v_rcp_f32_e32 v66, v66
	v_rcp_f32_e32 v67, v67
	v_add_f32_e32 v70, 1.0, v70
	v_add_f32_e32 v71, 1.0, v71
	v_rcp_f32_e32 v70, v70
	v_rcp_f32_e32 v71, v71
	v_pk_mul_f32 v[64:65], v[66:67], v[64:65]
	s_nop 0
	v_pk_mul_f32 v[48:49], v[48:49], v[64:65]
	v_pk_mul_f32 v[64:65], v[70:71], v[68:69]
	v_cvt_pk_bf16_f32 v48, v48, v49
	v_pk_mul_f32 v[50:51], v[50:51], v[64:65]
	v_lshlrev_b32_e32 v64, 16, v89
	v_cvt_pk_bf16_f32 v49, v50, v51
	v_mov_b32_e32 v236, v48
	v_mov_b32_e32 v237, v49
	v_lshlrev_b32_e32 v48, 16, v88
	v_mul_f32_e32 v49, 0xbfb8aa3b, v48
	v_exp_f32_e32 v50, v49
	v_and_b32_e32 v49, 0xffff0000, v88
	v_mul_f32_e32 v51, 0xbfb8aa3b, v49
	v_and_b32_e32 v65, 0xffff0000, v89
	v_exp_f32_e32 v51, v51
	v_mul_f32_e32 v66, 0xbfb8aa3b, v64
	v_mul_f32_e32 v67, 0xbfb8aa3b, v65
	v_exp_f32_e32 v66, v66
	v_exp_f32_e32 v67, v67
	v_add_f32_e32 v50, 1.0, v50
	v_add_f32_e32 v51, 1.0, v51
	v_rcp_f32_e32 v50, v50
	v_rcp_f32_e32 v51, v51
	v_add_f32_e32 v66, 1.0, v66
	v_add_f32_e32 v67, 1.0, v67
	v_rcp_f32_e32 v66, v66
	v_rcp_f32_e32 v67, v67
	v_pk_mul_f32 v[48:49], v[50:51], v[48:49]
	v_pk_mul_f32 v[50:51], v[54:55], v[0:1] op_sel_hi:[1,0]
	v_pk_mul_f32 v[48:49], v[52:53], v[48:49]
	v_pk_mul_f32 v[52:53], v[66:67], v[64:65]
	v_cvt_pk_bf16_f32 v48, v48, v49
	v_pk_mul_f32 v[50:51], v[50:51], v[52:53]
	v_lshlrev_b32_e32 v54, 16, v87
	v_cvt_pk_bf16_f32 v49, v50, v51
	v_mov_b32_e32 v238, v48
	v_mov_b32_e32 v239, v49
	s_nop 1
	v_permlane32_swap_b32 v236, v238
	v_permlane32_swap_b32 v237, v239
	global_store_dwordx4 v[226:227], v[236:239], off offset:64
	v_lshlrev_b32_e32 v48, 16, v86
	v_mul_f32_e32 v49, 0xbfb8aa3b, v48
	v_exp_f32_e32 v50, v49
	v_and_b32_e32 v49, 0xffff0000, v86
	v_mul_f32_e32 v51, 0xbfb8aa3b, v49
	v_and_b32_e32 v55, 0xffff0000, v87
	v_exp_f32_e32 v51, v51
	v_pk_mul_f32 v[52:53], v[56:57], v[0:1] op_sel_hi:[1,0]
	v_mul_f32_e32 v56, 0xbfb8aa3b, v54
	v_mul_f32_e32 v57, 0xbfb8aa3b, v55
	v_exp_f32_e32 v56, v56
	v_exp_f32_e32 v57, v57
	v_add_f32_e32 v50, 1.0, v50
	v_add_f32_e32 v51, 1.0, v51
	v_rcp_f32_e32 v50, v50
	v_rcp_f32_e32 v51, v51
	v_add_f32_e32 v56, 1.0, v56
	v_add_f32_e32 v57, 1.0, v57
	v_rcp_f32_e32 v56, v56
	v_rcp_f32_e32 v57, v57
	v_pk_mul_f32 v[48:49], v[50:51], v[48:49]
	v_pk_mul_f32 v[50:51], v[58:59], v[0:1] op_sel_hi:[1,0]
	v_pk_mul_f32 v[48:49], v[52:53], v[48:49]
	v_pk_mul_f32 v[52:53], v[56:57], v[54:55]
	v_cvt_pk_bf16_f32 v48, v48, v49
	v_pk_mul_f32 v[50:51], v[50:51], v[52:53]
	v_lshlrev_b32_e32 v54, 16, v85
	v_cvt_pk_bf16_f32 v49, v50, v51
	v_mov_b32_e32 v240, v48
	v_mov_b32_e32 v241, v49
	v_lshlrev_b32_e32 v48, 16, v84
	v_mul_f32_e32 v49, 0xbfb8aa3b, v48
	v_exp_f32_e32 v50, v49
	v_and_b32_e32 v49, 0xffff0000, v84
	v_mul_f32_e32 v51, 0xbfb8aa3b, v49
	v_and_b32_e32 v55, 0xffff0000, v85
	v_exp_f32_e32 v51, v51
	v_mul_f32_e32 v56, 0xbfb8aa3b, v54
	v_mul_f32_e32 v57, 0xbfb8aa3b, v55
	v_exp_f32_e32 v56, v56
	v_exp_f32_e32 v57, v57
	v_add_f32_e32 v50, 1.0, v50
	v_add_f32_e32 v51, 1.0, v51
	v_rcp_f32_e32 v50, v50
	v_rcp_f32_e32 v51, v51
	v_add_f32_e32 v56, 1.0, v56
	v_add_f32_e32 v57, 1.0, v57
	v_rcp_f32_e32 v56, v56
	v_rcp_f32_e32 v57, v57
	v_pk_mul_f32 v[52:53], v[60:61], v[0:1] op_sel_hi:[1,0]
	v_pk_mul_f32 v[48:49], v[50:51], v[48:49]
	v_pk_mul_f32 v[50:51], v[62:63], v[0:1] op_sel_hi:[1,0]
	v_pk_mul_f32 v[48:49], v[52:53], v[48:49]
	v_pk_mul_f32 v[52:53], v[56:57], v[54:55]
	v_cvt_pk_bf16_f32 v48, v48, v49
	v_pk_mul_f32 v[50:51], v[50:51], v[52:53]
	v_lshlrev_b32_e32 v52, 16, v83
	v_cvt_pk_bf16_f32 v49, v50, v51
	v_mov_b32_e32 v242, v48
	v_mov_b32_e32 v243, v49
	s_nop 1
	v_permlane32_swap_b32 v240, v242
; __device__ __forceinline__ float silu_f(float z) { return z * __builtin_amdgcn_rcpf(1.0f + __builtin_amdgcn_exp2f(-LOG2E * z)); }
; __device__ __forceinline__ float bf_lo(unsigned v) { return __uint_as_float(v << 16); }
; __device__ __forceinline__ float bf_hi(unsigned v) { return __uint_as_float(v & 0xffff0000u); }
; template <int MODE>
; __device__ __forceinline__ void attn_unit(const Params& P, LAS unsigned char* lds, const int b, const int h, const int qb) {
;     ...
;     if (FOX) {
; #pragma unroll
;         for (int d = 0; d < 4; ++d)
; #pragma unroll
;             for (int a = 0; a < 4; ++a) { const int d0 = 32 * d + 8 * a + 4 * hh; const u32x2 z2 = zv[d][a];
;                 const float o0 = O[d][4 * a] * inv1 * silu_f(bf_lo(z2.x)), o1 = O[d][4 * a + 1] * inv1 * silu_f(bf_hi(z2.x));
;                 const float o2 = O[d][4 * a + 2] * inv1 * silu_f(bf_lo(z2.y)), o3 = O[d][4 * a + 3] * inv1 * silu_f(bf_hi(z2.y));
;                 u32x2 ov; ov.x = cvt_pk_bf16(o0, o1); ov.y = cvt_pk_bf16(o2, o3); *(u32x2*)(mix + d0) = ov; }
	v_permlane32_swap_b32 v241, v243
	global_store_dwordx4 v[226:227], v[240:243], off offset:96
	v_lshlrev_b32_e32 v48, 16, v82
	v_mul_f32_e32 v49, 0xbfb8aa3b, v48
	v_exp_f32_e32 v50, v49
	v_and_b32_e32 v49, 0xffff0000, v82
	v_mul_f32_e32 v51, 0xbfb8aa3b, v49
	v_and_b32_e32 v53, 0xffff0000, v83
	v_exp_f32_e32 v51, v51
	v_mul_f32_e32 v54, 0xbfb8aa3b, v52
	v_mul_f32_e32 v55, 0xbfb8aa3b, v53
	v_exp_f32_e32 v54, v54
	v_exp_f32_e32 v55, v55
	v_add_f32_e32 v50, 1.0, v50
	v_add_f32_e32 v51, 1.0, v51
	v_rcp_f32_e32 v50, v50
	v_rcp_f32_e32 v51, v51
	v_add_f32_e32 v54, 1.0, v54
	v_add_f32_e32 v55, 1.0, v55
	v_rcp_f32_e32 v54, v54
	v_rcp_f32_e32 v55, v55
	v_pk_mul_f32 v[48:49], v[50:51], v[48:49]
	s_nop 0
	v_pk_mul_f32 v[32:33], v[32:33], v[48:49]
	v_pk_mul_f32 v[48:49], v[54:55], v[52:53]
	v_cvt_pk_bf16_f32 v32, v32, v33
	v_pk_mul_f32 v[34:35], v[34:35], v[48:49]
	v_lshlrev_b32_e32 v48, 16, v81
	v_cvt_pk_bf16_f32 v33, v34, v35
	v_mov_b32_e32 v236, v32
	v_mov_b32_e32 v237, v33
	v_lshlrev_b32_e32 v32, 16, v80
	v_mul_f32_e32 v33, 0xbfb8aa3b, v32
	v_exp_f32_e32 v34, v33
	v_and_b32_e32 v33, 0xffff0000, v80
	v_mul_f32_e32 v35, 0xbfb8aa3b, v33
	v_and_b32_e32 v49, 0xffff0000, v81
	v_exp_f32_e32 v35, v35
	v_mul_f32_e32 v50, 0xbfb8aa3b, v48
	v_mul_f32_e32 v51, 0xbfb8aa3b, v49
	v_exp_f32_e32 v50, v50
	v_exp_f32_e32 v51, v51
	v_add_f32_e32 v34, 1.0, v34
	v_add_f32_e32 v35, 1.0, v35
	v_rcp_f32_e32 v34, v34
	v_rcp_f32_e32 v35, v35
	v_add_f32_e32 v50, 1.0, v50
	v_add_f32_e32 v51, 1.0, v51
	v_rcp_f32_e32 v50, v50
	v_rcp_f32_e32 v51, v51
	v_pk_mul_f32 v[32:33], v[34:35], v[32:33]
	v_pk_mul_f32 v[34:35], v[38:39], v[0:1] op_sel_hi:[1,0]
	v_pk_mul_f32 v[32:33], v[36:37], v[32:33]
	v_pk_mul_f32 v[36:37], v[50:51], v[48:49]
	v_cvt_pk_bf16_f32 v32, v32, v33
	v_pk_mul_f32 v[34:35], v[34:35], v[36:37]
	v_and_b32_e32 v37, 0xffff0000, v15
	v_cvt_pk_bf16_f32 v33, v34, v35
	v_mov_b32_e32 v238, v32
	v_mov_b32_e32 v239, v33
	s_nop 1
	v_permlane32_swap_b32 v236, v238
	v_permlane32_swap_b32 v237, v239
	global_store_dwordx4 v[226:227], v[236:239], off offset:128
	v_lshlrev_b32_e32 v32, 16, v14
	v_mul_f32_e32 v33, 0xbfb8aa3b, v32
	v_exp_f32_e32 v34, v33
	v_and_b32_e32 v33, 0xffff0000, v14
	v_mul_f32_e32 v14, 0xbfb8aa3b, v33
	v_exp_f32_e32 v36, v14
	v_add_f32_e32 v14, 1.0, v34
	v_pk_mul_f32 v[34:35], v[40:41], v[0:1] op_sel_hi:[1,0]
	v_rcp_f32_e32 v14, v14
	v_add_f32_e32 v38, 1.0, v36
	v_lshlrev_b32_e32 v36, 16, v15
	v_mul_f32_e32 v15, 0xbfb8aa3b, v36
	v_exp_f32_e32 v39, v15
	v_mul_f32_e32 v15, 0xbfb8aa3b, v37
	v_exp_f32_e32 v40, v15
	v_rcp_f32_e32 v15, v38
	v_add_f32_e32 v38, 1.0, v39
	v_rcp_f32_e32 v38, v38
	v_add_f32_e32 v39, 1.0, v40
	v_rcp_f32_e32 v39, v39
	v_pk_mul_f32 v[14:15], v[14:15], v[32:33]
	v_pk_mul_f32 v[32:33], v[42:43], v[0:1] op_sel_hi:[1,0]
	v_pk_mul_f32 v[14:15], v[34:35], v[14:15]
	v_pk_mul_f32 v[34:35], v[38:39], v[36:37]
	v_cvt_pk_bf16_f32 v14, v14, v15
	v_pk_mul_f32 v[32:33], v[32:33], v[34:35]
	v_and_b32_e32 v35, 0xffff0000, v13
	v_cvt_pk_bf16_f32 v15, v32, v33
	v_mov_b32_e32 v240, v14
	v_mov_b32_e32 v241, v15
	v_lshlrev_b32_e32 v14, 16, v12
	v_mul_f32_e32 v15, 0xbfb8aa3b, v14
	v_exp_f32_e32 v32, v15
	v_and_b32_e32 v15, 0xffff0000, v12
	v_mul_f32_e32 v12, 0xbfb8aa3b, v15
	v_exp_f32_e32 v34, v12
	v_add_f32_e32 v12, 1.0, v32
	v_rcp_f32_e32 v12, v12
	v_pk_mul_f32 v[32:33], v[44:45], v[0:1] op_sel_hi:[1,0]
	v_add_f32_e32 v36, 1.0, v34
	v_lshlrev_b32_e32 v34, 16, v13
	v_mul_f32_e32 v13, 0xbfb8aa3b, v34
	v_exp_f32_e32 v37, v13
	v_mul_f32_e32 v13, 0xbfb8aa3b, v35
	v_exp_f32_e32 v38, v13
	v_rcp_f32_e32 v13, v36
	v_add_f32_e32 v36, 1.0, v37
	v_rcp_f32_e32 v36, v36
	v_add_f32_e32 v37, 1.0, v38
	v_rcp_f32_e32 v37, v37
	v_pk_mul_f32 v[12:13], v[12:13], v[14:15]
	v_pk_mul_f32 v[14:15], v[46:47], v[0:1] op_sel_hi:[1,0]
	v_pk_mul_f32 v[12:13], v[32:33], v[12:13]
	v_pk_mul_f32 v[32:33], v[36:37], v[34:35]
	v_cvt_pk_bf16_f32 v12, v12, v13
	v_pk_mul_f32 v[14:15], v[14:15], v[32:33]
	s_nop 0
	v_cvt_pk_bf16_f32 v13, v14, v15
	v_mov_b32_e32 v242, v12
	v_mov_b32_e32 v243, v13
	s_nop 1
	v_permlane32_swap_b32 v240, v242
	v_permlane32_swap_b32 v241, v243
	global_store_dwordx4 v[226:227], v[240:243], off offset:160
; __device__ __forceinline__ float silu_f(float z) { return z * __builtin_amdgcn_rcpf(1.0f + __builtin_amdgcn_exp2f(-LOG2E * z)); }
; __device__ __forceinline__ float bf_lo(unsigned v) { return __uint_as_float(v << 16); }
; __device__ __forceinline__ float bf_hi(unsigned v) { return __uint_as_float(v & 0xffff0000u); }
; template <int MODE>
; __device__ __forceinline__ void attn_unit(const Params& P, LAS unsigned char* lds, const int b, const int h, const int qb) {
;     ...
;     if (FOX) {
; #pragma unroll
;         for (int d = 0; d < 4; ++d)
; #pragma unroll
;             for (int a = 0; a < 4; ++a) { const int d0 = 32 * d + 8 * a + 4 * hh; const u32x2 z2 = zv[d][a];
;                 const float o0 = O[d][4 * a] * inv1 * silu_f(bf_lo(z2.x)), o1 = O[d][4 * a + 1] * inv1 * silu_f(bf_hi(z2.x));
;                 const float o2 = O[d][4 * a + 2] * inv1 * silu_f(bf_lo(z2.y)), o3 = O[d][4 * a + 3] * inv1 * silu_f(bf_hi(z2.y));
;                 u32x2 ov; ov.x = cvt_pk_bf16(o0, o1); ov.y = cvt_pk_bf16(o2, o3); *(u32x2*)(mix + d0) = ov; }
;         __syncthreads();
	v_lshlrev_b32_e32 v12, 16, v10
	v_mul_f32_e32 v13, 0xbfb8aa3b, v12
	v_exp_f32_e32 v14, v13
	v_and_b32_e32 v13, 0xffff0000, v10
	v_mul_f32_e32 v10, 0xbfb8aa3b, v13
	v_exp_f32_e32 v32, v10
	v_add_f32_e32 v10, 1.0, v14
	v_pk_mul_f32 v[14:15], v[16:17], v[0:1] op_sel_hi:[1,0]
	v_lshlrev_b32_e32 v16, 16, v11
	v_and_b32_e32 v17, 0xffff0000, v11
	v_mul_f32_e32 v11, 0xbfb8aa3b, v16
	v_exp_f32_e32 v33, v11
	v_mul_f32_e32 v11, 0xbfb8aa3b, v17
	v_exp_f32_e32 v34, v11
	v_add_f32_e32 v32, 1.0, v32
	v_rcp_f32_e32 v10, v10
	v_rcp_f32_e32 v11, v32
	v_add_f32_e32 v32, 1.0, v33
	v_add_f32_e32 v33, 1.0, v34
	v_rcp_f32_e32 v32, v32
	v_rcp_f32_e32 v33, v33
	v_pk_mul_f32 v[10:11], v[10:11], v[12:13]
	v_pk_mul_f32 v[12:13], v[18:19], v[0:1] op_sel_hi:[1,0]
	v_pk_mul_f32 v[10:11], v[14:15], v[10:11]
	v_pk_mul_f32 v[14:15], v[32:33], v[16:17]
	v_cvt_pk_bf16_f32 v10, v10, v11
	v_pk_mul_f32 v[12:13], v[12:13], v[14:15]
	v_and_b32_e32 v15, 0xffff0000, v9
	v_cvt_pk_bf16_f32 v11, v12, v13
	v_mov_b32_e32 v236, v10
	v_mov_b32_e32 v237, v11
	v_lshlrev_b32_e32 v10, 16, v8
	v_mul_f32_e32 v11, 0xbfb8aa3b, v10
	v_exp_f32_e32 v12, v11
	v_and_b32_e32 v11, 0xffff0000, v8
	v_mul_f32_e32 v8, 0xbfb8aa3b, v11
	v_exp_f32_e32 v14, v8
	v_add_f32_e32 v8, 1.0, v12
	v_rcp_f32_e32 v8, v8
	v_pk_mul_f32 v[12:13], v[20:21], v[0:1] op_sel_hi:[1,0]
	v_add_f32_e32 v16, 1.0, v14
	v_lshlrev_b32_e32 v14, 16, v9
	v_mul_f32_e32 v9, 0xbfb8aa3b, v14
	v_exp_f32_e32 v17, v9
	v_mul_f32_e32 v9, 0xbfb8aa3b, v15
	v_exp_f32_e32 v18, v9
	v_rcp_f32_e32 v9, v16
	v_add_f32_e32 v16, 1.0, v17
	v_rcp_f32_e32 v16, v16
	v_add_f32_e32 v17, 1.0, v18
	v_rcp_f32_e32 v17, v17
	v_pk_mul_f32 v[8:9], v[8:9], v[10:11]
	v_pk_mul_f32 v[10:11], v[22:23], v[0:1] op_sel_hi:[1,0]
	v_pk_mul_f32 v[8:9], v[12:13], v[8:9]
	v_pk_mul_f32 v[12:13], v[16:17], v[14:15]
	v_cvt_pk_bf16_f32 v8, v8, v9
	v_pk_mul_f32 v[10:11], v[10:11], v[12:13]
	v_and_b32_e32 v13, 0xffff0000, v7
	v_cvt_pk_bf16_f32 v9, v10, v11
	v_mov_b32_e32 v238, v8
	v_mov_b32_e32 v239, v9
	s_nop 1
	v_permlane32_swap_b32 v236, v238
	v_permlane32_swap_b32 v237, v239
	global_store_dwordx4 v[226:227], v[236:239], off offset:192
	v_lshlrev_b32_e32 v8, 16, v6
	v_mul_f32_e32 v9, 0xbfb8aa3b, v8
	v_exp_f32_e32 v10, v9
	v_and_b32_e32 v9, 0xffff0000, v6
	v_mul_f32_e32 v6, 0xbfb8aa3b, v9
	v_exp_f32_e32 v12, v6
	v_add_f32_e32 v6, 1.0, v10
	v_rcp_f32_e32 v6, v6
	v_pk_mul_f32 v[10:11], v[24:25], v[0:1] op_sel_hi:[1,0]
	v_add_f32_e32 v14, 1.0, v12
	v_lshlrev_b32_e32 v12, 16, v7
	v_mul_f32_e32 v7, 0xbfb8aa3b, v12
	v_exp_f32_e32 v15, v7
	v_mul_f32_e32 v7, 0xbfb8aa3b, v13
	v_exp_f32_e32 v16, v7
	v_rcp_f32_e32 v7, v14
	v_add_f32_e32 v14, 1.0, v15
	v_rcp_f32_e32 v14, v14
	v_add_f32_e32 v15, 1.0, v16
	v_rcp_f32_e32 v15, v15
	v_pk_mul_f32 v[6:7], v[6:7], v[8:9]
	v_pk_mul_f32 v[8:9], v[26:27], v[0:1] op_sel_hi:[1,0]
	v_pk_mul_f32 v[6:7], v[10:11], v[6:7]
	v_pk_mul_f32 v[10:11], v[14:15], v[12:13]
	v_cvt_pk_bf16_f32 v6, v6, v7
	v_pk_mul_f32 v[8:9], v[8:9], v[10:11]
	v_and_b32_e32 v11, 0xffff0000, v3
	v_cvt_pk_bf16_f32 v7, v8, v9
	v_mov_b32_e32 v240, v6
	v_mov_b32_e32 v241, v7
	v_lshlrev_b32_e32 v6, 16, v2
	v_mul_f32_e32 v7, 0xbfb8aa3b, v6
	v_exp_f32_e32 v8, v7
	v_and_b32_e32 v7, 0xffff0000, v2
	v_mul_f32_e32 v2, 0xbfb8aa3b, v7
	v_exp_f32_e32 v10, v2
	v_add_f32_e32 v2, 1.0, v8
	v_rcp_f32_e32 v2, v2
	v_pk_mul_f32 v[8:9], v[28:29], v[0:1] op_sel_hi:[1,0]
	v_add_f32_e32 v12, 1.0, v10
	v_lshlrev_b32_e32 v10, 16, v3
	v_mul_f32_e32 v3, 0xbfb8aa3b, v10
	v_exp_f32_e32 v13, v3
	v_mul_f32_e32 v3, 0xbfb8aa3b, v11
	v_exp_f32_e32 v14, v3
	v_rcp_f32_e32 v3, v12
	v_add_f32_e32 v12, 1.0, v13
	v_rcp_f32_e32 v12, v12
	v_add_f32_e32 v13, 1.0, v14
	v_rcp_f32_e32 v13, v13
	v_pk_mul_f32 v[2:3], v[2:3], v[6:7]
	v_pk_mul_f32 v[6:7], v[30:31], v[0:1] op_sel_hi:[1,0]
	v_pk_mul_f32 v[2:3], v[8:9], v[2:3]
	v_pk_mul_f32 v[8:9], v[12:13], v[10:11]
	v_cvt_pk_bf16_f32 v2, v2, v3
	v_pk_mul_f32 v[6:7], v[6:7], v[8:9]
	s_nop 0
	v_cvt_pk_bf16_f32 v3, v6, v7
	v_mov_b32_e32 v242, v2
	v_mov_b32_e32 v243, v3
	s_nop 1
	v_permlane32_swap_b32 v240, v242
	v_permlane32_swap_b32 v241, v243
	global_store_dwordx4 v[226:227], v[240:243], off offset:224
	s_barrier
